# swiglu epilogue: rstd scalings folded into the exp argument (g*(r*c)) and the denominator ((1+e)*x, x=ssq/D+eps), 2 fewer packed multiplies per element pair, all f32
# speedup vs baseline: 1.0097x; 1.0097x over previous
.LBB7_360:
	v_and_b32_e32 v131, 64, v163
	v_xor_b32_e32 v130, 16, v163
	v_add_u32_e32 v131, 64, v131
	v_cmp_lt_i32_e32 vcc, v130, v131
	v_lshl_add_u32 v132, s38, 8, v142
	v_ashrrev_i32_e32 v133, 31, v132
	v_cndmask_b32_e32 v130, v163, v130, vcc
	v_lshlrev_b32_e32 v183, 2, v130
	v_xor_b32_e32 v130, 32, v163
	v_cmp_lt_i32_e32 vcc, v130, v131
	v_or_b32_e32 v172, 16, v132
	v_ashrrev_i32_e32 v173, 31, v172
	v_cndmask_b32_e32 v130, v163, v130, vcc
	v_lshlrev_b32_e32 v181, 2, v130
	v_lshlrev_b64 v[130:131], 6, v[132:133]
	v_lshl_add_u64 v[130:131], v[144:145], 0, v[130:131]
	v_lshlrev_b64 v[172:173], 6, v[172:173]
	v_lshl_add_u64 v[172:173], v[144:145], 0, v[172:173]
	s_lshl_b32 s9, s10, 7
	s_mov_b32 s10, 0x358637bd
	v_mov_b64_e32 v[190:191], s[10:11]
	s_movk_i32 s10, 0x2000
	s_or_b32 s9, s9, s96
	s_ashr_i32 s16, s9, 6
	s_ashr_i32 s17, s16, 31
	s_mul_i32 s13, s38, 0x160000
	s_lshl_b64 s[16:17], s[16:17], 15
	s_add_u32 s9, s70, s13
	s_waitcnt vmcnt(0)
	v_mov_b64_e32 v[184:185], v[204:205]
	v_mov_b64_e32 v[186:187], v[206:207]
	v_mov_b32_e32 v170, v185
	v_mov_b32_e32 v171, v186
	v_mov_b32_e32 v185, v187
	v_pk_add_f32 v[170:171], v[170:171], v[184:185]
	v_mov_b64_e32 v[184:185], v[208:209]
	v_mov_b64_e32 v[186:187], v[210:211]
	v_mov_b32_e32 v172, v185
	v_mov_b32_e32 v173, v186
	v_mov_b32_e32 v185, v187
	v_pk_add_f32 v[172:173], v[172:173], v[184:185]
	v_mov_b32_e32 v185, v170
	v_mov_b32_e32 v184, v172
	v_mov_b32_e32 v170, v173
	v_pk_add_f32 v[170:171], v[184:185], v[170:171]
	v_mov_b32_e32 v173, v171
	s_nop 1
	v_permlane16_swap_b32_e32 v171, v173
	v_mov_b32_e32 v172, v170
	s_nop 1
	v_permlane16_swap_b32_e32 v170, v172
	s_waitcnt lgkmcnt(0)
	v_pk_add_f32 v[170:171], v[170:171], v[172:173]
	v_mov_b32_e32 v173, v171
	s_nop 1
	v_permlane32_swap_b32_e32 v171, v173
	v_mov_b32_e32 v172, v170
	s_nop 1
	v_permlane32_swap_b32_e32 v170, v172
	s_waitcnt lgkmcnt(0)
	v_pk_add_f32 v[170:171], v[170:171], v[172:173]
	s_nop 0
	v_pk_fma_f32 v[170:171], v[170:171], s[26:27], v[190:191] op_sel_hi:[1,0,0]
	v_mov_b64_e32 v[204:205], v[170:171]
	s_nop 0
	v_mul_f32_e32 v133, 0x4b800000, v171
	v_cmp_gt_f32_e64 s[42:43], s11, v171
	v_cmp_gt_f32_e32 vcc, s11, v170
	s_nop 0
	v_cndmask_b32_e64 v133, v171, v133, s[42:43]
	v_rsq_f32_e32 v133, v133
	s_nop 0
	v_mul_f32_e32 v171, 0x45800000, v133
	v_cndmask_b32_e64 v188, v133, v171, s[42:43]
	v_mul_f32_e32 v207, s30, v188
	v_mul_f32_e32 v133, 0x4b800000, v170
	v_cndmask_b32_e32 v133, v170, v133, vcc
	v_rsq_f32_e32 v133, v133
	s_nop 0
	v_mul_f32_e32 v170, 0x45800000, v133
	v_cndmask_b32_e32 v186, v133, v170, vcc
	v_mul_f32_e32 v206, s30, v186
	v_or_b32_e32 v170, 32, v132
	v_ashrrev_i32_e32 v171, 31, v170
	v_lshlrev_b64 v[170:171], 6, v[170:171]
	v_lshl_add_u64 v[170:171], v[144:145], 0, v[170:171]
	v_or_b32_e32 v132, 48, v132
	v_ashrrev_i32_e32 v133, 31, v132
	v_lshlrev_b64 v[132:133], 6, v[132:133]
	v_lshl_add_u64 v[132:133], v[144:145], 0, v[132:133]
	v_pk_mul_f32 v[122:123], v[126:127], v[122:123]
	v_pk_mul_f32 v[114:115], v[118:119], v[114:115]
	v_pk_mul_f32 v[106:107], v[110:111], v[106:107]
	v_pk_mul_f32 v[98:99], v[102:103], v[98:99]
	v_mov_b64_e32 v[192:193], v[212:213]
	v_mov_b64_e32 v[194:195], v[214:215]
	v_mov_b32_e32 v170, v193
	v_mov_b32_e32 v171, v194
	v_mov_b32_e32 v193, v195
	v_pk_add_f32 v[170:171], v[170:171], v[192:193]
	v_mov_b64_e32 v[192:193], v[216:217]
	v_mov_b64_e32 v[194:195], v[218:219]
	v_mov_b32_e32 v173, v170
	v_mov_b32_e32 v132, v193
	v_mov_b32_e32 v133, v194
	v_mov_b32_e32 v193, v195
	v_pk_add_f32 v[132:133], v[132:133], v[192:193]
	s_nop 0
	v_mov_b32_e32 v172, v132
	v_mov_b32_e32 v170, v133
	v_pk_add_f32 v[132:133], v[172:173], v[170:171]
	v_mov_b32_e32 v171, v133
	s_nop 1
	v_permlane16_swap_b32_e32 v133, v171
	v_mov_b32_e32 v170, v132
	s_nop 1
	v_permlane16_swap_b32_e32 v132, v170
	s_waitcnt lgkmcnt(0)
	v_pk_add_f32 v[132:133], v[132:133], v[170:171]
	v_mov_b32_e32 v171, v133
	s_nop 1
	v_permlane32_swap_b32_e32 v133, v171
	v_mov_b32_e32 v170, v132
	s_nop 1
	v_permlane32_swap_b32_e32 v132, v170
	s_waitcnt lgkmcnt(0)
	v_pk_add_f32 v[132:133], v[132:133], v[170:171]
	s_nop 0
	v_pk_fma_f32 v[132:133], v[132:133], s[26:27], v[190:191] op_sel_hi:[1,0,0]
	v_mov_b64_e32 v[212:213], v[132:133]
	s_nop 0
	v_mul_f32_e32 v170, 0x4b800000, v133
	v_cmp_gt_f32_e64 s[42:43], s11, v133
	v_cmp_gt_f32_e32 vcc, s11, v132
	s_nop 0
	v_cndmask_b32_e64 v133, v133, v170, s[42:43]
	v_rsq_f32_e32 v133, v133
	s_nop 0
	v_mul_f32_e32 v170, 0x45800000, v133
	v_cndmask_b32_e64 v184, v133, v170, s[42:43]
	v_mul_f32_e32 v215, s30, v184
	v_mul_f32_e32 v133, 0x4b800000, v132
	v_cndmask_b32_e32 v132, v132, v133, vcc
	v_rsq_f32_e32 v132, v132
	s_nop 0
	v_mul_f32_e32 v133, 0x45800000, v132
	v_cndmask_b32_e32 v182, v132, v133, vcc
	v_mul_f32_e32 v214, s30, v182
	v_add_co_u32_e32 v170, vcc, s10, v130
	s_mul_hi_i32 s10, s38, 0x160000
	s_nop 0
	v_addc_co_u32_e32 v171, vcc, 0, v131, vcc
	s_addc_u32 s10, s71, s10
	s_add_u32 s16, s9, s16
	s_addc_u32 s17, s10, s17
	v_pk_mul_f32 v[90:91], v[94:95], v[90:91]
	v_pk_mul_f32 v[82:83], v[86:87], v[82:83]
	v_pk_mul_f32 v[74:75], v[78:79], v[74:75]
	v_pk_mul_f32 v[66:67], v[70:71], v[66:67]
	v_mov_b64_e32 v[130:131], v[220:221]
	v_mov_b64_e32 v[132:133], v[222:223]
	v_mov_b32_e32 v172, v131
	v_mov_b32_e32 v173, v132
	v_mov_b32_e32 v131, v133
	v_pk_add_f32 v[172:173], v[172:173], v[130:131]
	v_mov_b64_e32 v[130:131], v[224:225]
	v_mov_b64_e32 v[132:133], v[226:227]
	v_mov_b32_e32 v192, v131
	v_mov_b32_e32 v193, v132
	v_mov_b32_e32 v131, v133
	v_pk_add_f32 v[130:131], v[192:193], v[130:131]
	v_mov_b32_e32 v133, v172
	v_mov_b32_e32 v132, v130
	v_mov_b32_e32 v172, v131
	v_pk_add_f32 v[130:131], v[132:133], v[172:173]
	v_mov_b32_e32 v133, v131
	s_nop 1
	v_permlane16_swap_b32_e32 v131, v133
	v_mov_b32_e32 v132, v130
	s_nop 1
	v_permlane16_swap_b32_e32 v130, v132
	s_waitcnt lgkmcnt(0)
	v_pk_add_f32 v[130:131], v[130:131], v[132:133]
	v_mov_b32_e32 v133, v131
	s_nop 1
	v_permlane32_swap_b32_e32 v131, v133
	v_mov_b32_e32 v132, v130
	s_nop 1
	v_permlane32_swap_b32_e32 v130, v132
	s_waitcnt lgkmcnt(0)
	v_pk_add_f32 v[130:131], v[130:131], v[132:133]
	s_nop 0
	v_pk_fma_f32 v[130:131], v[130:131], s[26:27], v[190:191] op_sel_hi:[1,0,0]
	v_mov_b64_e32 v[220:221], v[130:131]
	s_nop 0
	v_mul_f32_e32 v132, 0x4b800000, v131
	v_cmp_gt_f32_e64 s[42:43], s11, v131
	v_cmp_gt_f32_e32 vcc, s11, v130
	s_nop 0
	v_cndmask_b32_e64 v131, v131, v132, s[42:43]
	v_rsq_f32_e32 v131, v131
	s_nop 0
	v_mul_f32_e32 v132, 0x45800000, v131
	v_cndmask_b32_e64 v180, v131, v132, s[42:43]
	v_mul_f32_e32 v223, s30, v180
	v_mul_f32_e32 v131, 0x4b800000, v130
	v_cndmask_b32_e32 v130, v130, v131, vcc
	v_rsq_f32_e32 v130, v130
	s_nop 0
	v_mul_f32_e32 v131, 0x45800000, v130
	v_cndmask_b32_e32 v178, v130, v131, vcc
	v_mul_f32_e32 v222, s30, v178
	v_pk_mul_f32 v[58:59], v[62:63], v[58:59]
	v_pk_mul_f32 v[50:51], v[54:55], v[50:51]
	v_pk_mul_f32 v[42:43], v[46:47], v[42:43]
	v_pk_mul_f32 v[34:35], v[38:39], v[34:35]
	v_mov_b64_e32 v[130:131], v[228:229]
	v_mov_b64_e32 v[132:133], v[230:231]
	v_mov_b32_e32 v172, v131
	v_mov_b32_e32 v173, v132
	v_mov_b32_e32 v131, v133
	v_pk_add_f32 v[192:193], v[172:173], v[130:131]
	v_mov_b64_e32 v[130:131], v[232:233]
	v_mov_b64_e32 v[132:133], v[234:235]
	v_mov_b32_e32 v170, v131
	v_mov_b32_e32 v171, v132
	v_mov_b32_e32 v131, v133
	v_pk_add_f32 v[130:131], v[170:171], v[130:131]
	v_pk_mul_f32 v[170:171], v[126:127], v[206:207] op_sel:[0,1] op_sel_hi:[1,1]
	v_mov_b64_e32 v[126:127], v[128:129]
	v_exp_f32_e32 v170, v170
	v_pk_mul_f32 v[128:129], v[126:127], v[206:207] op_sel:[0,1] op_sel_hi:[1,1]
	v_exp_f32_e32 v171, v171
	v_exp_f32_e32 v128, v128
	v_exp_f32_e32 v129, v129
	v_pk_mul_f32 v[124:125], v[126:127], v[124:125]
	v_pk_fma_f32 v[170:171], v[170:171], v[204:205], v[204:205] op_sel:[0,1,1] op_sel_hi:[1,1,1]
	v_mov_b32_e32 v132, v130
	v_pk_fma_f32 v[128:129], v[128:129], v[204:205], v[204:205] op_sel:[0,1,1] op_sel_hi:[1,1,1]
	v_rcp_f32_e32 v170, v170
	v_rcp_f32_e32 v171, v171
	v_rcp_f32_e32 v128, v128
	v_rcp_f32_e32 v129, v129
	v_mov_b32_e32 v133, v192
	v_pk_mul_f32 v[122:123], v[122:123], v[170:171]
	v_mov_b32_e32 v192, v131
	v_pk_mul_f32 v[124:125], v[124:125], v[128:129]
	v_cvt_pk_bf16_f32 v122, v122, v123
	v_pk_add_f32 v[130:131], v[132:133], v[192:193]
	v_cvt_pk_bf16_f32 v123, v124, v125
	v_pk_mul_f32 v[124:125], v[118:119], v[206:207] op_sel:[0,1] op_sel_hi:[1,1]
	v_mov_b32_e32 v133, v131
	s_nop 1
	v_permlane16_swap_b32_e32 v131, v133
	v_exp_f32_e32 v124, v124
	v_exp_f32_e32 v125, v125
	v_mov_b32_e32 v132, v130
	s_nop 1
	v_permlane16_swap_b32_e32 v130, v132
	v_pk_fma_f32 v[124:125], v[124:125], v[204:205], v[204:205] op_sel:[0,1,1] op_sel_hi:[1,1,1]
	s_nop 0
	v_rcp_f32_e32 v124, v124
	v_rcp_f32_e32 v125, v125
	s_waitcnt lgkmcnt(0)
	v_pk_add_f32 v[130:131], v[130:131], v[132:133]
	v_mov_b32_e32 v133, v131
	s_nop 1
	v_permlane32_swap_b32_e32 v131, v133
	v_mov_b32_e32 v132, v130
	s_nop 1
	v_permlane32_swap_b32_e32 v130, v132
	v_pk_mul_f32 v[114:115], v[114:115], v[124:125]
	s_waitcnt lgkmcnt(0)
	v_pk_add_f32 v[130:131], v[130:131], v[132:133]
	v_cvt_pk_bf16_f32 v124, v114, v115
	v_mov_b64_e32 v[114:115], v[120:121]
	v_pk_fma_f32 v[130:131], v[130:131], s[26:27], v[190:191] op_sel_hi:[1,0,0]
	v_mov_b64_e32 v[228:229], v[130:131]
	v_pk_mul_f32 v[118:119], v[114:115], v[206:207] op_sel:[0,1] op_sel_hi:[1,1]
	v_pk_mul_f32 v[114:115], v[114:115], v[116:117]
	v_exp_f32_e32 v118, v118
	v_exp_f32_e32 v119, v119
	v_mul_f32_e32 v132, 0x4b800000, v131
	v_cmp_gt_f32_e64 s[42:43], s11, v131
	v_cmp_gt_f32_e32 vcc, s11, v130
	v_pk_fma_f32 v[118:119], v[118:119], v[204:205], v[204:205] op_sel:[0,1,1] op_sel_hi:[1,1,1]
	v_cndmask_b32_e64 v131, v131, v132, s[42:43]
	v_rcp_f32_e32 v118, v118
	v_rcp_f32_e32 v119, v119
	v_rsq_f32_e32 v131, v131
	v_pk_mul_f32 v[114:115], v[114:115], v[118:119]
	s_nop 0
	v_cvt_pk_bf16_f32 v125, v114, v115
	v_lshl_add_u64 v[114:115], s[16:17], 0, v[146:147]
	v_lshl_add_u64 v[114:115], v[114:115], 0, v[0:1]
	global_store_dwordx4 v[114:115], v[122:125], off nt
	v_pk_mul_f32 v[114:115], v[110:111], v[206:207] op_sel:[0,0] op_sel_hi:[1,0]
	v_mov_b64_e32 v[110:111], v[112:113]
	v_exp_f32_e32 v114, v114
	v_pk_mul_f32 v[112:113], v[110:111], v[206:207] op_sel:[0,0] op_sel_hi:[1,0]
	v_exp_f32_e32 v115, v115
	v_exp_f32_e32 v112, v112
	v_exp_f32_e32 v113, v113
	v_pk_mul_f32 v[108:109], v[110:111], v[108:109]
	v_pk_fma_f32 v[114:115], v[114:115], v[204:205], v[204:205] op_sel:[0,0,0] op_sel_hi:[1,0,0]
	v_pk_fma_f32 v[112:113], v[112:113], v[204:205], v[204:205] op_sel:[0,0,0] op_sel_hi:[1,0,0]
	v_rcp_f32_e32 v114, v114
	v_rcp_f32_e32 v115, v115
	v_rcp_f32_e32 v112, v112
	v_rcp_f32_e32 v113, v113
	v_mul_f32_e32 v132, 0x45800000, v131
	v_pk_mul_f32 v[106:107], v[106:107], v[114:115]
	v_cndmask_b32_e64 v132, v131, v132, s[42:43]
	v_mul_f32_e32 v231, s30, v132
	v_pk_mul_f32 v[108:109], v[108:109], v[112:113]
	v_cvt_pk_bf16_f32 v106, v106, v107
	v_cvt_pk_bf16_f32 v107, v108, v109
	v_pk_mul_f32 v[108:109], v[102:103], v[206:207] op_sel:[0,0] op_sel_hi:[1,0]
	v_exp_f32_e32 v108, v108
	v_exp_f32_e32 v109, v109
	v_pk_mul_f32 v[26:27], v[30:31], v[26:27]
	v_pk_fma_f32 v[108:109], v[108:109], v[204:205], v[204:205] op_sel:[0,0,0] op_sel_hi:[1,0,0]
	v_rcp_f32_e32 v108, v108
	v_rcp_f32_e32 v109, v109
	v_pk_mul_f32 v[18:19], v[22:23], v[18:19]
	v_mul_f32_e32 v131, 0x4b800000, v130
	v_cndmask_b32_e32 v130, v130, v131, vcc
	v_pk_mul_f32 v[98:99], v[98:99], v[108:109]
	v_rsq_f32_e32 v130, v130
	v_cvt_pk_bf16_f32 v108, v98, v99
	v_mov_b64_e32 v[98:99], v[104:105]
	v_pk_mul_f32 v[102:103], v[98:99], v[206:207] op_sel:[0,0] op_sel_hi:[1,0]
	v_pk_mul_f32 v[98:99], v[98:99], v[100:101]
	v_exp_f32_e32 v102, v102
	v_exp_f32_e32 v103, v103
	v_mul_f32_e32 v131, 0x45800000, v130
	v_cndmask_b32_e32 v130, v130, v131, vcc
	v_mul_f32_e32 v230, s30, v130
	v_pk_fma_f32 v[102:103], v[102:103], v[204:205], v[204:205] op_sel:[0,0,0] op_sel_hi:[1,0,0]
	v_rcp_f32_e32 v102, v102
	v_rcp_f32_e32 v103, v103
	v_pk_mul_f32 v[10:11], v[14:15], v[10:11]
	v_pk_mul_f32 v[98:99], v[98:99], v[102:103]
	v_cvt_pk_bf16_f32 v109, v98, v99
	v_lshl_add_u64 v[98:99], s[16:17], 0, v[148:149]
	v_lshl_add_u64 v[98:99], v[98:99], 0, v[0:1]
	global_store_dwordx4 v[98:99], v[106:109], off nt
	v_pk_mul_f32 v[98:99], v[94:95], v[214:215] op_sel:[0,1] op_sel_hi:[1,1]
	v_mov_b64_e32 v[94:95], v[96:97]
	v_exp_f32_e32 v98, v98
	v_pk_mul_f32 v[96:97], v[94:95], v[214:215] op_sel:[0,1] op_sel_hi:[1,1]
	v_exp_f32_e32 v99, v99
	v_exp_f32_e32 v96, v96
	v_exp_f32_e32 v97, v97
	v_pk_mul_f32 v[92:93], v[94:95], v[92:93]
	v_pk_fma_f32 v[98:99], v[98:99], v[212:213], v[212:213] op_sel:[0,1,1] op_sel_hi:[1,1,1]
	v_pk_fma_f32 v[96:97], v[96:97], v[212:213], v[212:213] op_sel:[0,1,1] op_sel_hi:[1,1,1]
	v_rcp_f32_e32 v98, v98
	v_rcp_f32_e32 v99, v99
	v_rcp_f32_e32 v96, v96
	v_rcp_f32_e32 v97, v97
	v_pk_mul_f32 v[2:3], v[6:7], v[2:3]
	v_pk_mul_f32 v[90:91], v[90:91], v[98:99]
	v_pk_mul_f32 v[92:93], v[92:93], v[96:97]
	v_cvt_pk_bf16_f32 v90, v90, v91
	s_andn2_b64 vcc, exec, s[40:41]
	v_cvt_pk_bf16_f32 v91, v92, v93
	v_pk_mul_f32 v[92:93], v[86:87], v[214:215] op_sel:[0,1] op_sel_hi:[1,1]
	s_nop 0
	v_exp_f32_e32 v92, v92
	v_exp_f32_e32 v93, v93
	s_nop 0
	v_pk_fma_f32 v[92:93], v[92:93], v[212:213], v[212:213] op_sel:[0,1,1] op_sel_hi:[1,1,1]
	s_nop 0
	v_rcp_f32_e32 v92, v92
	v_rcp_f32_e32 v93, v93
	s_nop 0
	v_pk_mul_f32 v[82:83], v[82:83], v[92:93]
	s_nop 0
	v_cvt_pk_bf16_f32 v92, v82, v83
	v_mov_b64_e32 v[82:83], v[88:89]
	s_nop 0
	v_pk_mul_f32 v[86:87], v[82:83], v[214:215] op_sel:[0,1] op_sel_hi:[1,1]
	v_pk_mul_f32 v[82:83], v[82:83], v[84:85]
	v_exp_f32_e32 v86, v86
	v_exp_f32_e32 v87, v87
	s_nop 0
	v_pk_fma_f32 v[86:87], v[86:87], v[212:213], v[212:213] op_sel:[0,1,1] op_sel_hi:[1,1,1]
	s_nop 0
	v_rcp_f32_e32 v86, v86
	v_rcp_f32_e32 v87, v87
	s_nop 0
	v_pk_mul_f32 v[82:83], v[82:83], v[86:87]
	s_nop 0
	v_cvt_pk_bf16_f32 v93, v82, v83
	v_lshl_add_u64 v[82:83], s[16:17], 0, v[150:151]
	v_lshl_add_u64 v[82:83], v[82:83], 0, v[0:1]
	global_store_dwordx4 v[82:83], v[90:93], off nt
	v_pk_mul_f32 v[82:83], v[78:79], v[214:215] op_sel:[0,0] op_sel_hi:[1,0]
	v_mov_b64_e32 v[78:79], v[80:81]
	v_exp_f32_e32 v82, v82
	v_pk_mul_f32 v[80:81], v[78:79], v[214:215] op_sel:[0,0] op_sel_hi:[1,0]
	v_exp_f32_e32 v83, v83
	v_exp_f32_e32 v80, v80
	v_exp_f32_e32 v81, v81
	v_pk_mul_f32 v[76:77], v[78:79], v[76:77]
	v_pk_fma_f32 v[82:83], v[82:83], v[212:213], v[212:213] op_sel:[0,0,0] op_sel_hi:[1,0,0]
	v_pk_fma_f32 v[80:81], v[80:81], v[212:213], v[212:213] op_sel:[0,0,0] op_sel_hi:[1,0,0]
	v_rcp_f32_e32 v82, v82
	v_rcp_f32_e32 v83, v83
	v_rcp_f32_e32 v80, v80
	v_rcp_f32_e32 v81, v81
	v_pk_mul_f32 v[74:75], v[74:75], v[82:83]
	s_nop 0
	v_cvt_pk_bf16_f32 v74, v74, v75
	v_pk_mul_f32 v[76:77], v[76:77], v[80:81]
	s_nop 0
	v_cvt_pk_bf16_f32 v75, v76, v77
	v_pk_mul_f32 v[76:77], v[70:71], v[214:215] op_sel:[0,0] op_sel_hi:[1,0]
	s_nop 0
	v_exp_f32_e32 v76, v76
	v_exp_f32_e32 v77, v77
	s_nop 0
	v_pk_fma_f32 v[76:77], v[76:77], v[212:213], v[212:213] op_sel:[0,0,0] op_sel_hi:[1,0,0]
	s_nop 0
	v_rcp_f32_e32 v76, v76
	v_rcp_f32_e32 v77, v77
	s_nop 0
	v_pk_mul_f32 v[66:67], v[66:67], v[76:77]
	s_nop 0
	v_cvt_pk_bf16_f32 v76, v66, v67
	v_mov_b64_e32 v[66:67], v[72:73]
	s_nop 0
	v_pk_mul_f32 v[70:71], v[66:67], v[214:215] op_sel:[0,0] op_sel_hi:[1,0]
	v_pk_mul_f32 v[66:67], v[66:67], v[68:69]
	v_exp_f32_e32 v70, v70
	v_exp_f32_e32 v71, v71
	s_nop 0
	v_pk_fma_f32 v[70:71], v[70:71], v[212:213], v[212:213] op_sel:[0,0,0] op_sel_hi:[1,0,0]
	s_nop 0
	v_rcp_f32_e32 v70, v70
	v_rcp_f32_e32 v71, v71
	s_nop 0
	v_pk_mul_f32 v[66:67], v[66:67], v[70:71]
	s_nop 0
	v_cvt_pk_bf16_f32 v77, v66, v67
	v_lshl_add_u64 v[66:67], s[16:17], 0, v[152:153]
	v_lshl_add_u64 v[66:67], v[66:67], 0, v[0:1]
	global_store_dwordx4 v[66:67], v[74:77], off nt
	v_pk_mul_f32 v[66:67], v[62:63], v[222:223] op_sel:[0,1] op_sel_hi:[1,1]
	v_mov_b64_e32 v[62:63], v[64:65]
	v_exp_f32_e32 v66, v66
	v_pk_mul_f32 v[64:65], v[62:63], v[222:223] op_sel:[0,1] op_sel_hi:[1,1]
	v_exp_f32_e32 v67, v67
	v_exp_f32_e32 v64, v64
	v_exp_f32_e32 v65, v65
	v_pk_mul_f32 v[60:61], v[62:63], v[60:61]
	v_pk_fma_f32 v[66:67], v[66:67], v[220:221], v[220:221] op_sel:[0,1,1] op_sel_hi:[1,1,1]
	v_pk_fma_f32 v[64:65], v[64:65], v[220:221], v[220:221] op_sel:[0,1,1] op_sel_hi:[1,1,1]
	v_rcp_f32_e32 v66, v66
	v_rcp_f32_e32 v67, v67
	v_rcp_f32_e32 v64, v64
	v_rcp_f32_e32 v65, v65
	v_pk_mul_f32 v[58:59], v[58:59], v[66:67]
	s_nop 0
	v_cvt_pk_bf16_f32 v58, v58, v59
	v_pk_mul_f32 v[60:61], v[60:61], v[64:65]
	s_nop 0
	v_cvt_pk_bf16_f32 v59, v60, v61
	v_pk_mul_f32 v[60:61], v[54:55], v[222:223] op_sel:[0,1] op_sel_hi:[1,1]
	s_nop 0
	v_exp_f32_e32 v60, v60
	v_exp_f32_e32 v61, v61
	s_nop 0
	v_pk_fma_f32 v[60:61], v[60:61], v[220:221], v[220:221] op_sel:[0,1,1] op_sel_hi:[1,1,1]
	s_nop 0
	v_rcp_f32_e32 v60, v60
	v_rcp_f32_e32 v61, v61
	s_nop 0
	v_pk_mul_f32 v[50:51], v[50:51], v[60:61]
	s_nop 0
	v_cvt_pk_bf16_f32 v60, v50, v51
	v_mov_b64_e32 v[50:51], v[56:57]
	s_nop 0
	v_pk_mul_f32 v[54:55], v[50:51], v[222:223] op_sel:[0,1] op_sel_hi:[1,1]
	v_pk_mul_f32 v[50:51], v[50:51], v[52:53]
	v_exp_f32_e32 v54, v54
	v_exp_f32_e32 v55, v55
	s_nop 0
	v_pk_fma_f32 v[54:55], v[54:55], v[220:221], v[220:221] op_sel:[0,1,1] op_sel_hi:[1,1,1]
	s_nop 0
	v_rcp_f32_e32 v54, v54
	v_rcp_f32_e32 v55, v55
	s_nop 0
	v_pk_mul_f32 v[50:51], v[50:51], v[54:55]
	s_nop 0
	v_cvt_pk_bf16_f32 v61, v50, v51
	v_lshl_add_u64 v[50:51], s[16:17], 0, v[154:155]
	v_lshl_add_u64 v[50:51], v[50:51], 0, v[0:1]
	global_store_dwordx4 v[50:51], v[58:61], off nt
	v_pk_mul_f32 v[50:51], v[46:47], v[222:223] op_sel:[0,0] op_sel_hi:[1,0]
	v_mov_b64_e32 v[46:47], v[48:49]
	v_exp_f32_e32 v50, v50
	v_pk_mul_f32 v[48:49], v[46:47], v[222:223] op_sel:[0,0] op_sel_hi:[1,0]
	v_exp_f32_e32 v51, v51
	v_exp_f32_e32 v48, v48
	v_exp_f32_e32 v49, v49
	v_pk_mul_f32 v[44:45], v[46:47], v[44:45]
	v_pk_fma_f32 v[50:51], v[50:51], v[220:221], v[220:221] op_sel:[0,0,0] op_sel_hi:[1,0,0]
	v_pk_fma_f32 v[48:49], v[48:49], v[220:221], v[220:221] op_sel:[0,0,0] op_sel_hi:[1,0,0]
	v_rcp_f32_e32 v50, v50
	v_rcp_f32_e32 v51, v51
	v_rcp_f32_e32 v48, v48
	v_rcp_f32_e32 v49, v49
	v_pk_mul_f32 v[42:43], v[42:43], v[50:51]
	s_nop 0
	v_cvt_pk_bf16_f32 v42, v42, v43
	v_pk_mul_f32 v[44:45], v[44:45], v[48:49]
	s_nop 0
	v_cvt_pk_bf16_f32 v43, v44, v45
	v_pk_mul_f32 v[44:45], v[38:39], v[222:223] op_sel:[0,0] op_sel_hi:[1,0]
	s_nop 0
	v_exp_f32_e32 v44, v44
	v_exp_f32_e32 v45, v45
	s_nop 0
	v_pk_fma_f32 v[44:45], v[44:45], v[220:221], v[220:221] op_sel:[0,0,0] op_sel_hi:[1,0,0]
	s_nop 0
	v_rcp_f32_e32 v44, v44
	v_rcp_f32_e32 v45, v45
	s_nop 0
	v_pk_mul_f32 v[34:35], v[34:35], v[44:45]
	s_nop 0
	v_cvt_pk_bf16_f32 v44, v34, v35
	v_mov_b64_e32 v[34:35], v[40:41]
	s_nop 0
	v_pk_mul_f32 v[38:39], v[34:35], v[222:223] op_sel:[0,0] op_sel_hi:[1,0]
	v_pk_mul_f32 v[34:35], v[34:35], v[36:37]
	v_exp_f32_e32 v38, v38
	v_exp_f32_e32 v39, v39
	s_nop 0
	v_pk_fma_f32 v[38:39], v[38:39], v[220:221], v[220:221] op_sel:[0,0,0] op_sel_hi:[1,0,0]
	s_nop 0
	v_rcp_f32_e32 v38, v38
	v_rcp_f32_e32 v39, v39
	s_nop 0
	v_pk_mul_f32 v[34:35], v[34:35], v[38:39]
	s_nop 0
	v_cvt_pk_bf16_f32 v45, v34, v35
	v_lshl_add_u64 v[34:35], s[16:17], 0, v[156:157]
	v_lshl_add_u64 v[34:35], v[34:35], 0, v[0:1]
	global_store_dwordx4 v[34:35], v[42:45], off nt
	v_pk_mul_f32 v[34:35], v[30:31], v[230:231] op_sel:[0,1] op_sel_hi:[1,1]
	v_mov_b64_e32 v[30:31], v[32:33]
	v_exp_f32_e32 v34, v34
	v_pk_mul_f32 v[32:33], v[30:31], v[230:231] op_sel:[0,1] op_sel_hi:[1,1]
	v_exp_f32_e32 v35, v35
	v_exp_f32_e32 v32, v32
	v_exp_f32_e32 v33, v33
	v_pk_mul_f32 v[28:29], v[30:31], v[28:29]
	v_pk_fma_f32 v[34:35], v[34:35], v[228:229], v[228:229] op_sel:[0,1,1] op_sel_hi:[1,1,1]
	v_pk_fma_f32 v[32:33], v[32:33], v[228:229], v[228:229] op_sel:[0,1,1] op_sel_hi:[1,1,1]
	v_rcp_f32_e32 v34, v34
	v_rcp_f32_e32 v35, v35
	v_rcp_f32_e32 v32, v32
	v_rcp_f32_e32 v33, v33
	v_pk_mul_f32 v[26:27], v[26:27], v[34:35]
	s_nop 0
	v_cvt_pk_bf16_f32 v26, v26, v27
	v_pk_mul_f32 v[28:29], v[28:29], v[32:33]
	s_nop 0
	v_cvt_pk_bf16_f32 v27, v28, v29
	v_pk_mul_f32 v[28:29], v[22:23], v[230:231] op_sel:[0,1] op_sel_hi:[1,1]
	s_nop 0
	v_exp_f32_e32 v28, v28
	v_exp_f32_e32 v29, v29
	s_nop 0
	v_pk_fma_f32 v[28:29], v[28:29], v[228:229], v[228:229] op_sel:[0,1,1] op_sel_hi:[1,1,1]
	s_nop 0
	v_rcp_f32_e32 v28, v28
	v_rcp_f32_e32 v29, v29
	s_nop 0
	v_pk_mul_f32 v[18:19], v[18:19], v[28:29]
	s_nop 0
	v_cvt_pk_bf16_f32 v28, v18, v19
	v_mov_b64_e32 v[18:19], v[24:25]
	s_nop 0
	v_pk_mul_f32 v[22:23], v[18:19], v[230:231] op_sel:[0,1] op_sel_hi:[1,1]
	v_pk_mul_f32 v[18:19], v[18:19], v[20:21]
	v_exp_f32_e32 v22, v22
	v_exp_f32_e32 v23, v23
	s_nop 0
	v_pk_fma_f32 v[22:23], v[22:23], v[228:229], v[228:229] op_sel:[0,1,1] op_sel_hi:[1,1,1]
	s_nop 0
	v_rcp_f32_e32 v22, v22
	v_rcp_f32_e32 v23, v23
	s_nop 0
	v_pk_mul_f32 v[18:19], v[18:19], v[22:23]
	s_nop 0
	v_cvt_pk_bf16_f32 v29, v18, v19
	v_lshl_add_u64 v[18:19], s[16:17], 0, v[158:159]
	v_lshl_add_u64 v[18:19], v[18:19], 0, v[0:1]
	global_store_dwordx4 v[18:19], v[26:29], off nt
	v_pk_mul_f32 v[18:19], v[14:15], v[230:231] op_sel:[0,0] op_sel_hi:[1,0]
	v_mov_b64_e32 v[14:15], v[16:17]
	v_exp_f32_e32 v18, v18
	v_pk_mul_f32 v[16:17], v[14:15], v[230:231] op_sel:[0,0] op_sel_hi:[1,0]
	v_exp_f32_e32 v19, v19
	v_exp_f32_e32 v16, v16
	v_exp_f32_e32 v17, v17
	v_pk_mul_f32 v[12:13], v[14:15], v[12:13]
	v_pk_fma_f32 v[18:19], v[18:19], v[228:229], v[228:229] op_sel:[0,0,0] op_sel_hi:[1,0,0]
	v_pk_fma_f32 v[16:17], v[16:17], v[228:229], v[228:229] op_sel:[0,0,0] op_sel_hi:[1,0,0]
	v_rcp_f32_e32 v18, v18
	v_rcp_f32_e32 v19, v19
	v_rcp_f32_e32 v16, v16
	v_rcp_f32_e32 v17, v17
	v_pk_mul_f32 v[10:11], v[10:11], v[18:19]
	s_nop 0
	v_cvt_pk_bf16_f32 v10, v10, v11
	v_pk_mul_f32 v[12:13], v[12:13], v[16:17]
	s_nop 0
	v_cvt_pk_bf16_f32 v11, v12, v13
	v_pk_mul_f32 v[12:13], v[6:7], v[230:231] op_sel:[0,0] op_sel_hi:[1,0]
	s_nop 0
	v_exp_f32_e32 v12, v12
	v_exp_f32_e32 v13, v13
	s_nop 0
	v_pk_fma_f32 v[12:13], v[12:13], v[228:229], v[228:229] op_sel:[0,0,0] op_sel_hi:[1,0,0]
	s_nop 0
	v_rcp_f32_e32 v12, v12
	v_rcp_f32_e32 v13, v13
	s_nop 0
	v_pk_mul_f32 v[2:3], v[2:3], v[12:13]
	s_nop 0
	v_cvt_pk_bf16_f32 v12, v2, v3
	v_mov_b64_e32 v[2:3], v[8:9]
	s_nop 0
	v_pk_mul_f32 v[6:7], v[2:3], v[230:231] op_sel:[0,0] op_sel_hi:[1,0]
	v_pk_mul_f32 v[2:3], v[2:3], v[4:5]
	v_exp_f32_e32 v6, v6
	v_exp_f32_e32 v7, v7
	s_nop 0
	v_pk_fma_f32 v[6:7], v[6:7], v[228:229], v[228:229] op_sel:[0,0,0] op_sel_hi:[1,0,0]
	s_nop 0
	v_rcp_f32_e32 v6, v6
	v_rcp_f32_e32 v7, v7
	s_nop 0
	v_pk_mul_f32 v[2:3], v[2:3], v[6:7]
	s_nop 0
	v_cvt_pk_bf16_f32 v13, v2, v3
	v_lshl_add_u64 v[2:3], s[16:17], 0, v[160:161]
	v_lshl_add_u64 v[2:3], v[2:3], 0, v[0:1]
	global_store_dwordx4 v[2:3], v[10:13], off nt
	s_mov_b64 s[16:17], -1
	s_cbranch_vccnz .LBB7_352
	s_andn2_b64 vcc, exec, s[50:51]
	s_cbranch_vccnz .LBB7_351
	s_branch .LBB7_351
